# P3 rope+conv: rope-k loads issued together with rope-q loads at the top of the row loop (one exposed latency less per row), on v26
# speedup vs baseline: 1.0006x; 1.0006x over previous
; __device__ __forceinline__ void post_u_rows(const Ptrs& P, int G, int bid) {
;     ...
;     for (int r = bid * 8 + wave; r < NT; r += G * 8) {
;         const int pos = r & (SEQ - 1); h16* u = U + (size_t)r * DINP;
;         float cs[8], sn[8];
; #pragma unroll
;         for (int e = 0; e < 8; ++e) { const float ang = (float)pos * inv[e];
;             double rev = (double)ang * 0.15915494309189535; rev -= __builtin_rint(rev);
;             const float rf = (float)rev; cs[e] = __builtin_amdgcn_cosf(rf); sn[e] = __builtin_amdgcn_sinf(rf); }
; #pragma unroll
;         for (int rd = 0; rd < 2; ++rd) {
;             const int base = rd == 0 ? OFF_Q + 128 * hsel : (hsel < 2 ? OFF_KC + 128 * hsel : (hsel < 4 ? OFF_KS + 128 * (hsel - 2) : OFF_KW + 128 * (hsel - 4)));
;             if (rd == 0 || hsel < 6) {
;                 const half8 x1 = *(const half8*)(u + base + 8 * c8), x2 = *(const half8*)(u + base + 64 + 8 * c8); half8 o1, o2;
; #pragma unroll
;                 for (int e = 0; e < 8; ++e) { const float a = (float)x1[e], bq = (float)x2[e]; o1[e] = (h16)(a * cs[e] - bq * sn[e]); o2[e] = (h16)(bq * cs[e] + a * sn[e]); }
;                 *(half8*)(u + base + 8 * c8) = o1; *(half8*)(u + base + 64 + 8 * c8) = o2; }
.LBB0_342:
	v_lshl_add_u64 v[70:71], s[24:25], 0, v[140:141]
	v_add_co_u32_e32 v96, vcc, s0, v70
	v_and_b32_e32 v86, 0x1fff, v130
	s_nop 0
	v_addc_co_u32_e32 v97, vcc, 0, v71, vcc
	global_load_dwordx4 v[88:91], v[96:97], off offset:2048
	global_load_dwordx4 v[92:95], v[96:97], off offset:2176
	v_lshl_add_u64 v[178:179], s[24:25], 0, v[142:143]
	v_add_co_u32_e32 v178, vcc, 0xe564000, v178
	s_nop 1
	v_addc_co_u32_e32 v179, vcc, 0, v179, vcc
	global_load_dwordx4 v[170:173], v[178:179], off
	global_load_dwordx4 v[174:177], v[178:179], off offset:128
	v_cvt_f32_u32_e32 v70, v86
	v_mul_f32_e32 v71, v148, v70
	v_mul_f32_e32 v72, v149, v70
	v_mul_f32_e32 v74, v150, v70
	v_mul_f32_e32 v76, v151, v70
	v_mul_f32_e32 v78, v152, v70
	v_mul_f32_e32 v80, v153, v70
	v_mul_f32_e32 v82, v154, v70
	v_mul_f32_e32 v84, v156, v70
	v_cvt_f64_f32_e32 v[70:71], v71
	v_cvt_f64_f32_e32 v[72:73], v72
	v_cvt_f64_f32_e32 v[74:75], v74
	v_cvt_f64_f32_e32 v[76:77], v76
	v_cvt_f64_f32_e32 v[78:79], v78
	v_mul_f64 v[98:99], v[70:71], s[28:29]
	v_mul_f64 v[100:101], v[72:73], s[28:29]
	v_mul_f64 v[102:103], v[74:75], s[28:29]
	v_mul_f64 v[104:105], v[76:77], s[28:29]
	v_mul_f64 v[106:107], v[78:79], s[28:29]
	v_rndne_f64_e32 v[98:99], v[98:99]
	v_rndne_f64_e32 v[100:101], v[100:101]
	v_rndne_f64_e32 v[102:103], v[102:103]
	v_rndne_f64_e32 v[104:105], v[104:105]
	v_rndne_f64_e32 v[106:107], v[106:107]
	v_fma_f64 v[70:71], v[70:71], s[28:29], -v[98:99]
	v_fma_f64 v[72:73], v[72:73], s[28:29], -v[100:101]
	v_fma_f64 v[74:75], v[74:75], s[28:29], -v[102:103]
	v_fma_f64 v[76:77], v[76:77], s[28:29], -v[104:105]
	v_fma_f64 v[78:79], v[78:79], s[28:29], -v[106:107]
	v_cvt_f32_f64_e32 v71, v[70:71]
	v_cvt_f32_f64_e32 v72, v[72:73]
	v_cvt_f32_f64_e32 v73, v[74:75]
	v_cvt_f32_f64_e32 v76, v[76:77]
	v_cvt_f64_f32_e32 v[80:81], v80
	v_cvt_f32_f64_e32 v77, v[78:79]
	v_sin_f32_e32 v74, v71
	v_sin_f32_e32 v75, v72
	v_sin_f32_e32 v78, v73
	v_sin_f32_e32 v79, v76
	v_cvt_f64_f32_e32 v[82:83], v82
	v_mul_f64 v[108:109], v[80:81], s[28:29]
	v_cos_f32_e32 v70, v71
	v_cos_f32_e32 v71, v72
	v_cos_f32_e32 v72, v73
	v_cos_f32_e32 v73, v76
	v_mul_f64 v[110:111], v[82:83], s[28:29]
	v_rndne_f64_e32 v[108:109], v[108:109]
	v_rndne_f64_e32 v[110:111], v[110:111]
	v_fma_f64 v[80:81], v[80:81], s[28:29], -v[108:109]
	v_fma_f64 v[82:83], v[82:83], s[28:29], -v[110:111]
	v_cvt_f32_f64_e32 v80, v[80:81]
	v_cvt_f64_f32_e32 v[84:85], v84
	v_cvt_f32_f64_e32 v81, v[82:83]
	v_sin_f32_e32 v82, v77
	v_sin_f32_e32 v83, v80
	v_mul_f64 v[112:113], v[84:85], s[28:29]
	v_cos_f32_e32 v76, v77
	v_cos_f32_e32 v77, v80
	v_rndne_f64_e32 v[112:113], v[112:113]
	v_fma_f64 v[84:85], v[84:85], s[28:29], -v[112:113]
	v_cvt_f32_f64_e32 v85, v[84:85]
	v_cos_f32_e32 v80, v81
	v_sin_f32_e32 v84, v81
	v_cos_f32_e32 v81, v85
	v_sin_f32_e32 v85, v85
	s_waitcnt vmcnt(3)
	v_cvt_f32_f16_e32 v98, v88
	v_cvt_f32_f16_sdwa v99, v88 dst_sel:DWORD dst_unused:UNUSED_PAD src0_sel:WORD_1
	s_waitcnt vmcnt(2)
	v_cvt_f32_f16_e32 v100, v92
	v_cvt_f32_f16_sdwa v101, v92 dst_sel:DWORD dst_unused:UNUSED_PAD src0_sel:WORD_1
	v_cvt_f32_f16_e32 v102, v89
	v_cvt_f32_f16_sdwa v103, v89 dst_sel:DWORD dst_unused:UNUSED_PAD src0_sel:WORD_1
	v_cvt_f32_f16_e32 v104, v93
	v_cvt_f32_f16_sdwa v105, v93 dst_sel:DWORD dst_unused:UNUSED_PAD src0_sel:WORD_1
	v_pk_mul_f32 v[88:89], v[74:75], v[98:99]
	v_pk_mul_f32 v[92:93], v[74:75], v[100:101]
	v_pk_mul_f32 v[106:107], v[78:79], v[102:103]
	v_pk_fma_f32 v[88:89], v[70:71], v[100:101], v[88:89]
	v_pk_fma_f32 v[92:93], v[70:71], v[98:99], v[92:93] neg_lo:[0,0,1] neg_hi:[0,0,1]
	v_pk_fma_f32 v[98:99], v[72:73], v[104:105], v[106:107]
	v_cvt_f32_f16_e32 v100, v90
	v_cvt_f32_f16_sdwa v101, v90 dst_sel:DWORD dst_unused:UNUSED_PAD src0_sel:WORD_1
	v_cvt_pk_f16_f32 v88, v88, v89
	v_cvt_pk_f16_f32 v89, v98, v99
	v_pk_mul_f32 v[98:99], v[78:79], v[104:105]
	v_cvt_f32_f16_e32 v104, v94
	v_cvt_f32_f16_sdwa v105, v94 dst_sel:DWORD dst_unused:UNUSED_PAD src0_sel:WORD_1
	v_pk_fma_f32 v[98:99], v[72:73], v[102:103], v[98:99] neg_lo:[0,0,1] neg_hi:[0,0,1]
	v_cvt_pk_f16_f32 v92, v92, v93
	v_cvt_pk_f16_f32 v93, v98, v99
	v_pk_mul_f32 v[98:99], v[82:83], v[100:101]
	v_cvt_f32_f16_e32 v102, v91
	v_pk_fma_f32 v[98:99], v[76:77], v[104:105], v[98:99]
	v_cvt_f32_f16_sdwa v103, v91 dst_sel:DWORD dst_unused:UNUSED_PAD src0_sel:WORD_1
	v_cvt_pk_f16_f32 v90, v98, v99
	v_pk_mul_f32 v[98:99], v[82:83], v[104:105]
	v_cvt_f32_f16_e32 v104, v95
	v_cvt_f32_f16_sdwa v105, v95 dst_sel:DWORD dst_unused:UNUSED_PAD src0_sel:WORD_1
	v_pk_fma_f32 v[94:95], v[76:77], v[100:101], v[98:99] neg_lo:[0,0,1] neg_hi:[0,0,1]
	v_pk_mul_f32 v[98:99], v[84:85], v[102:103]
	v_cvt_pk_f16_f32 v94, v94, v95
	v_pk_fma_f32 v[98:99], v[80:81], v[104:105], v[98:99]
	s_nop 0
	v_cvt_pk_f16_f32 v91, v98, v99
	v_pk_mul_f32 v[98:99], v[84:85], v[104:105]
	s_nop 0
	v_pk_fma_f32 v[98:99], v[80:81], v[102:103], v[98:99] neg_lo:[0,0,1] neg_hi:[0,0,1]
	s_nop 0
	v_cvt_pk_f16_f32 v95, v98, v99
	global_store_dwordx4 v[96:97], v[92:95], off offset:2048
	global_store_dwordx4 v[96:97], v[88:91], off offset:2176
	s_and_saveexec_b64 s[4:5], s[8:9]
	s_cbranch_execz .LBB0_344
; __device__ __forceinline__ void post_u_rows(const Ptrs& P, int G, int bid) {
;     ...
;         for (int rd = 0; rd < 2; ++rd) {
;             const int base = rd == 0 ? OFF_Q + 128 * hsel : (hsel < 2 ? OFF_KC + 128 * hsel : (hsel < 4 ? OFF_KS + 128 * (hsel - 2) : OFF_KW + 128 * (hsel - 4)));
;             if (rd == 0 || hsel < 6) {
;                 const half8 x1 = *(const half8*)(u + base + 8 * c8), x2 = *(const half8*)(u + base + 64 + 8 * c8); half8 o1, o2;
; #pragma unroll
;                 for (int e = 0; e < 8; ++e) { const float a = (float)x1[e], bq = (float)x2[e]; o1[e] = (h16)(a * cs[e] - bq * sn[e]); o2[e] = (h16)(bq * cs[e] + a * sn[e]); }
;                 *(half8*)(u + base + 8 * c8) = o1; *(half8*)(u + base + 64 + 8 * c8) = o2; }
	v_lshl_add_u64 v[88:89], s[24:25], 0, v[142:143]
	v_add_co_u32_e32 v96, vcc, 0xe564000, v88
	s_nop 1
	v_addc_co_u32_e32 v97, vcc, 0, v89, vcc
	s_waitcnt vmcnt(2)
	v_mov_b32_e32 v88, v170
	v_mov_b32_e32 v89, v171
	v_mov_b32_e32 v90, v172
	v_mov_b32_e32 v91, v173
	v_mov_b32_e32 v92, v174
	v_mov_b32_e32 v93, v175
	v_mov_b32_e32 v94, v176
	v_mov_b32_e32 v95, v177
	v_cvt_f32_f16_e32 v98, v88
	v_cvt_f32_f16_e32 v100, v92
	v_cvt_f32_f16_sdwa v101, v92 dst_sel:DWORD dst_unused:UNUSED_PAD src0_sel:WORD_1
	v_cvt_f32_f16_e32 v92, v93
	v_cvt_f32_f16_sdwa v93, v93 dst_sel:DWORD dst_unused:UNUSED_PAD src0_sel:WORD_1
	v_cvt_f32_f16_e32 v104, v94
	v_cvt_f32_f16_sdwa v105, v94 dst_sel:DWORD dst_unused:UNUSED_PAD src0_sel:WORD_1
	v_cvt_f32_f16_e32 v94, v95
	v_cvt_f32_f16_sdwa v95, v95 dst_sel:DWORD dst_unused:UNUSED_PAD src0_sel:WORD_1
	v_cvt_f32_f16_sdwa v99, v88 dst_sel:DWORD dst_unused:UNUSED_PAD src0_sel:WORD_1
	v_cvt_f32_f16_e32 v88, v89
	v_cvt_f32_f16_sdwa v89, v89 dst_sel:DWORD dst_unused:UNUSED_PAD src0_sel:WORD_1
	v_cvt_f32_f16_e32 v102, v90
	v_cvt_f32_f16_sdwa v103, v90 dst_sel:DWORD dst_unused:UNUSED_PAD src0_sel:WORD_1
	v_cvt_f32_f16_e32 v90, v91
	v_cvt_f32_f16_sdwa v91, v91 dst_sel:DWORD dst_unused:UNUSED_PAD src0_sel:WORD_1
	v_pk_mul_f32 v[106:107], v[70:71], v[100:101]
	v_pk_mul_f32 v[100:101], v[74:75], v[100:101]
	v_pk_mul_f32 v[108:109], v[72:73], v[92:93]
	v_pk_mul_f32 v[92:93], v[78:79], v[92:93]
	v_pk_mul_f32 v[110:111], v[76:77], v[104:105]
	v_pk_mul_f32 v[104:105], v[82:83], v[104:105]
	v_pk_mul_f32 v[112:113], v[80:81], v[94:95]
	v_pk_mul_f32 v[94:95], v[84:85], v[94:95]
	v_pk_fma_f32 v[74:75], v[74:75], v[98:99], v[106:107]
	v_pk_fma_f32 v[98:99], v[70:71], v[98:99], v[100:101] neg_lo:[0,0,1] neg_hi:[0,0,1]
	v_pk_fma_f32 v[72:73], v[72:73], v[88:89], v[92:93] neg_lo:[0,0,1] neg_hi:[0,0,1]
	v_pk_fma_f32 v[76:77], v[76:77], v[102:103], v[104:105] neg_lo:[0,0,1] neg_hi:[0,0,1]
	v_pk_fma_f32 v[80:81], v[80:81], v[90:91], v[94:95] neg_lo:[0,0,1] neg_hi:[0,0,1]
	v_pk_fma_f32 v[78:79], v[78:79], v[88:89], v[108:109]
	v_pk_fma_f32 v[82:83], v[82:83], v[102:103], v[110:111]
	v_pk_fma_f32 v[84:85], v[84:85], v[90:91], v[112:113]
	v_cvt_pk_f16_f32 v70, v74, v75
	v_cvt_pk_f16_f32 v74, v98, v99
	v_cvt_pk_f16_f32 v75, v72, v73
	v_cvt_pk_f16_f32 v76, v76, v77
	v_cvt_pk_f16_f32 v77, v80, v81
	v_cvt_pk_f16_f32 v71, v78, v79
	v_cvt_pk_f16_f32 v72, v82, v83
	v_cvt_pk_f16_f32 v73, v84, v85
	global_store_dwordx4 v[96:97], v[74:77], off
	global_store_dwordx4 v[96:97], v[70:73], off offset:128
